# m8 variant: every XCD runs the fp8 half of the input projection first (no parity split)
# baseline (speedup 1.0000x reference)
; __global__ void __launch_bounds__(NWAVES * 64, 2) mk_fwd(Args args) {
;     ...
;         G1_BF16(); G1_FP8();
.LBB0_358:
	s_mov_b32 s99, 0
	s_cmp_lt_i32 s94, 2
	s_cselect_b64 s[0:1], -1, 0
	s_cmp_gt_i32 s95, 1
	s_cselect_b64 s[4:5], -1, 0
	s_and_b64 s[0:1], s[0:1], s[4:5]
	s_andn2_b64 vcc, exec, s[0:1]
	s_cbranch_vccnz .LBB0_500
